# speedup vs baseline: 1.0232x; 1.0003x over previous
; #define LAS __attribute__((address_space(3)))
; __device__ __forceinline__ void fcum_phase(ArgP a, LAS unsigned char* lds, const int tid, const int bid) {
;     if (bid >= NHEAD) return;
;     const int h = bid;
;     const float* LOGF = (const float*)(a->ws + WS_LOGF); double* F = (double*)(a->ws + WS_F) + (size_t)h * SEQ;
;     LAS double* tot = (LAS double*)lds;
;     float v[32];
; #pragma unroll
;     for (int i = 0; i < 32; ++i) v[i] = LOGF[(size_t)(32 * tid + i) * 8 + h];
;     double s = 0.0;
; #pragma unroll
;     for (int i = 0; i < 32; ++i) s += (double)v[i];
;     tot[tid] = s;
.LBB0_379:
	s_and_b64 vcc, exec, s[0:1]
	s_cbranch_vccz .LBB0_468
	v_readlane_b32 s0, v255, 27
	s_cmp_gt_i32 s0, 0
	s_mov_b64 s[0:1], -1
	s_cbranch_scc0 .LBB0_471
	s_ashr_i32 s55, s54, 31
	s_cmp_lt_i32 s54, 8
	s_cbranch_scc0 .LBB0_401
	s_lshl_b64 s[0:1], s[54:55], 16
	s_waitcnt vmcnt(0) lgkmcnt(0)
	s_add_u32 s0, s72, s0
	s_addc_u32 s1, s73, s1
	v_lshlrev_b32_e32 v0, 5, v184
	s_add_u32 s0, s0, 0x8700000
	s_addc_u32 s1, s1, 0
	v_ashrrev_i32_e32 v1, 31, v0
	v_lshlrev_b32_e32 v60, 2, v184
	global_load_dword v2, v60, s[0:1]
	s_add_u32 s0, s0, 0x800
	s_addc_u32 s1, s1, 0
	global_load_dword v3, v60, s[0:1]
	s_add_u32 s0, s0, 0x800
	s_addc_u32 s1, s1, 0
	global_load_dword v4, v60, s[0:1]
	s_add_u32 s0, s0, 0x800
	s_addc_u32 s1, s1, 0
	global_load_dword v5, v60, s[0:1]
	s_add_u32 s0, s0, 0x800
	s_addc_u32 s1, s1, 0
	global_load_dword v6, v60, s[0:1]
	s_add_u32 s0, s0, 0x800
	s_addc_u32 s1, s1, 0
	global_load_dword v7, v60, s[0:1]
	s_add_u32 s0, s0, 0x800
	s_addc_u32 s1, s1, 0
	global_load_dword v8, v60, s[0:1]
	s_add_u32 s0, s0, 0x800
	s_addc_u32 s1, s1, 0
	global_load_dword v9, v60, s[0:1]
	s_add_u32 s0, s0, 0x800
	s_addc_u32 s1, s1, 0
	global_load_dword v10, v60, s[0:1]
	s_add_u32 s0, s0, 0x800
	s_addc_u32 s1, s1, 0
	global_load_dword v11, v60, s[0:1]
	s_add_u32 s0, s0, 0x800
	s_addc_u32 s1, s1, 0
	global_load_dword v12, v60, s[0:1]
	s_add_u32 s0, s0, 0x800
	s_addc_u32 s1, s1, 0
	global_load_dword v13, v60, s[0:1]
	s_add_u32 s0, s0, 0x800
	s_addc_u32 s1, s1, 0
	global_load_dword v14, v60, s[0:1]
	s_add_u32 s0, s0, 0x800
	s_addc_u32 s1, s1, 0
	global_load_dword v15, v60, s[0:1]
	s_add_u32 s0, s0, 0x800
	s_addc_u32 s1, s1, 0
	global_load_dword v16, v60, s[0:1]
	s_add_u32 s0, s0, 0x800
	s_addc_u32 s1, s1, 0
	global_load_dword v17, v60, s[0:1]
	s_add_u32 s0, s0, 0x800
	s_addc_u32 s1, s1, 0
	global_load_dword v18, v60, s[0:1]
	s_add_u32 s0, s0, 0x800
	s_addc_u32 s1, s1, 0
	global_load_dword v19, v60, s[0:1]
	s_add_u32 s0, s0, 0x800
	s_addc_u32 s1, s1, 0
	global_load_dword v20, v60, s[0:1]
	s_add_u32 s0, s0, 0x800
	s_addc_u32 s1, s1, 0
	global_load_dword v21, v60, s[0:1]
	s_add_u32 s0, s0, 0x800
	s_addc_u32 s1, s1, 0
	global_load_dword v22, v60, s[0:1]
	s_add_u32 s0, s0, 0x800
	s_addc_u32 s1, s1, 0
	global_load_dword v23, v60, s[0:1]
	s_add_u32 s0, s0, 0x800
	s_addc_u32 s1, s1, 0
	global_load_dword v24, v60, s[0:1]
	s_add_u32 s0, s0, 0x800
	s_addc_u32 s1, s1, 0
	global_load_dword v25, v60, s[0:1]
	s_add_u32 s0, s0, 0x800
	s_addc_u32 s1, s1, 0
	global_load_dword v26, v60, s[0:1]
	s_add_u32 s0, s0, 0x800
	s_addc_u32 s1, s1, 0
	global_load_dword v27, v60, s[0:1]
	s_add_u32 s0, s0, 0x800
	s_addc_u32 s1, s1, 0
	global_load_dword v28, v60, s[0:1]
	s_add_u32 s0, s0, 0x800
	s_addc_u32 s1, s1, 0
	global_load_dword v29, v60, s[0:1]
	s_add_u32 s0, s0, 0x800
	s_addc_u32 s1, s1, 0
	global_load_dword v30, v60, s[0:1]
	s_add_u32 s0, s0, 0x800
	s_addc_u32 s1, s1, 0
	global_load_dword v31, v60, s[0:1]
	s_add_u32 s0, s0, 0x800
	s_addc_u32 s1, s1, 0
	global_load_dword v32, v60, s[0:1]
	s_add_u32 s0, s0, 0x800
	s_addc_u32 s1, s1, 0
	global_load_dword v33, v60, s[0:1]
	v_lshrrev_b32_e32 v34, 5, v184
	v_bfe_u32 v35, v184, 2, 3
	v_and_b32_e32 v36, 7, v34
	v_xor_b32_e32 v35, v35, v36
	v_and_b32_e32 v36, 3, v184
	v_lshlrev_b32_e32 v36, 2, v36
	v_lshl_or_b32 v35, v35, 4, v36
	v_lshl_or_b32 v35, v34, 7, v35
	v_add_u32_e32 v36, 0x8000, v35
	v_and_b32_e32 v50, 7, v184
	v_lshlrev_b32_e32 v50, 4, v50
	v_lshl_or_b32 v50, v184, 7, v50
	v_mov_b32_e32 v42, v50
	v_xor_b32_e32 v43, 0x10, v50
	v_xor_b32_e32 v44, 0x20, v50
	v_xor_b32_e32 v45, 0x30, v50
	v_xor_b32_e32 v46, 0x40, v50
	v_xor_b32_e32 v47, 0x50, v50
	v_xor_b32_e32 v48, 0x60, v50
	v_xor_b32_e32 v49, 0x70, v50
	s_waitcnt vmcnt(31)
	ds_write_b32 v35, v2 offset:8192
	s_waitcnt vmcnt(30)
	ds_write_b32 v35, v3 offset:10240
	s_waitcnt vmcnt(29)
	ds_write_b32 v35, v4 offset:12288
	s_waitcnt vmcnt(28)
	ds_write_b32 v35, v5 offset:14336
	s_waitcnt vmcnt(27)
	ds_write_b32 v35, v6 offset:16384
	s_waitcnt vmcnt(26)
	ds_write_b32 v35, v7 offset:18432
	s_waitcnt vmcnt(25)
	ds_write_b32 v35, v8 offset:20480
	s_waitcnt vmcnt(24)
	ds_write_b32 v35, v9 offset:22528
	s_waitcnt vmcnt(23)
	ds_write_b32 v35, v10 offset:24576
	s_waitcnt vmcnt(22)
	ds_write_b32 v35, v11 offset:26624
	s_waitcnt vmcnt(21)
	ds_write_b32 v35, v12 offset:28672
	s_waitcnt vmcnt(20)
	ds_write_b32 v35, v13 offset:30720
	s_waitcnt vmcnt(19)
	ds_write_b32 v35, v14 offset:32768
	s_waitcnt vmcnt(18)
	ds_write_b32 v35, v15 offset:34816
	s_waitcnt vmcnt(17)
	ds_write_b32 v35, v16 offset:36864
	s_waitcnt vmcnt(16)
	ds_write_b32 v35, v17 offset:38912
	s_waitcnt vmcnt(15)
	ds_write_b32 v36, v18 offset:8192
	s_waitcnt vmcnt(14)
	ds_write_b32 v36, v19 offset:10240
	s_waitcnt vmcnt(13)
	ds_write_b32 v36, v20 offset:12288
	s_waitcnt vmcnt(12)
	ds_write_b32 v36, v21 offset:14336
	s_waitcnt vmcnt(11)
	ds_write_b32 v36, v22 offset:16384
	s_waitcnt vmcnt(10)
	ds_write_b32 v36, v23 offset:18432
	s_waitcnt vmcnt(9)
	ds_write_b32 v36, v24 offset:20480
	s_waitcnt vmcnt(8)
	ds_write_b32 v36, v25 offset:22528
	s_waitcnt vmcnt(7)
	ds_write_b32 v36, v26 offset:24576
	s_waitcnt vmcnt(6)
	ds_write_b32 v36, v27 offset:26624
	s_waitcnt vmcnt(5)
	ds_write_b32 v36, v28 offset:28672
	s_waitcnt vmcnt(4)
	ds_write_b32 v36, v29 offset:30720
	s_waitcnt vmcnt(3)
	ds_write_b32 v36, v30 offset:32768
	s_waitcnt vmcnt(2)
	ds_write_b32 v36, v31 offset:34816
	s_waitcnt vmcnt(1)
	ds_write_b32 v36, v32 offset:36864
	s_waitcnt vmcnt(0)
	ds_write_b32 v36, v33 offset:38912
	s_waitcnt lgkmcnt(0)
	s_barrier
; __device__ __forceinline__ void fcum_phase(ArgP a, LAS unsigned char* lds, const int tid, const int bid) {
;     ...
;     for (int i = 0; i < 32; ++i) v[i] = LOGF[(size_t)(32 * tid + i) * 8 + h];
;     double s = 0.0;
; #pragma unroll
;     for (int i = 0; i < 32; ++i) s += (double)v[i];
;     tot[tid] = s;
;     __syncthreads();
;     int cur = 0;
;     for (int d = 1; d < NTHR; d <<= 1) {
;         double x = tot[cur * NTHR + tid]; if (tid >= d) x += tot[cur * NTHR + tid - d];
;         tot[(cur ^ 1) * NTHR + tid] = x; cur ^= 1;
;         __syncthreads();
;     }
	ds_read_b128 v[18:21], v42 offset:8192
	ds_read_b128 v[22:25], v43 offset:8192
	ds_read_b128 v[26:29], v44 offset:8192
	ds_read_b128 v[30:33], v45 offset:8192
	ds_read_b128 v[66:69], v46 offset:8192
	ds_read_b128 v[10:13], v47 offset:8192
	ds_read_b128 v[52:55], v48 offset:8192
	ds_read_b128 v[56:59], v49 offset:8192
	s_waitcnt lgkmcnt(0)
	v_mov_b32_e32 v14, v52
	v_mov_b32_e32 v16, v53
	v_mov_b32_e32 v70, v54
	v_mov_b32_e32 v71, v55
	v_mov_b32_e32 v4, v56
	v_mov_b32_e32 v5, v57
	v_mov_b32_e32 v72, v58
	v_mov_b32_e32 v73, v59
	v_cvt_f64_f32_e32 v[64:65], v18
	v_add_f64 v[2:3], v[64:65], 0
	v_cvt_f64_f32_e32 v[62:63], v19
	v_add_f64 v[2:3], v[2:3], v[62:63]
	v_cvt_f64_f32_e32 v[58:59], v20
	v_add_f64 v[2:3], v[2:3], v[58:59]
	v_cvt_f64_f32_e32 v[60:61], v21
	v_add_f64 v[2:3], v[2:3], v[60:61]
	v_cvt_f64_f32_e32 v[54:55], v22
	v_add_f64 v[2:3], v[2:3], v[54:55]
	v_cvt_f64_f32_e32 v[56:57], v23
	v_add_f64 v[2:3], v[2:3], v[56:57]
	v_cvt_f64_f32_e32 v[50:51], v24
	v_add_f64 v[2:3], v[2:3], v[50:51]
	v_cvt_f64_f32_e32 v[52:53], v25
	v_add_f64 v[2:3], v[2:3], v[52:53]
	v_cvt_f64_f32_e32 v[46:47], v26
	v_add_f64 v[2:3], v[2:3], v[46:47]
	v_cvt_f64_f32_e32 v[48:49], v27
	v_add_f64 v[2:3], v[2:3], v[48:49]
	v_cvt_f64_f32_e32 v[42:43], v28
	v_add_f64 v[2:3], v[2:3], v[42:43]
	v_cvt_f64_f32_e32 v[44:45], v29
	v_add_f64 v[2:3], v[2:3], v[44:45]
	v_cvt_f64_f32_e32 v[38:39], v30
	v_add_f64 v[2:3], v[2:3], v[38:39]
	v_cvt_f64_f32_e32 v[40:41], v31
	v_add_f64 v[2:3], v[2:3], v[40:41]
	v_cvt_f64_f32_e32 v[34:35], v32
	v_add_f64 v[2:3], v[2:3], v[34:35]
	v_cvt_f64_f32_e32 v[36:37], v33
	v_add_f64 v[2:3], v[2:3], v[36:37]
	v_cmp_lt_i32_e32 vcc, 0, v184
	v_cvt_f64_f32_e32 v[30:31], v66
	v_add_f64 v[2:3], v[2:3], v[30:31]
	v_cvt_f64_f32_e32 v[32:33], v67
	v_add_f64 v[2:3], v[2:3], v[32:33]
	v_cvt_f64_f32_e32 v[26:27], v68
	v_add_f64 v[2:3], v[2:3], v[26:27]
	v_cvt_f64_f32_e32 v[28:29], v69
	v_add_f64 v[2:3], v[2:3], v[28:29]
	v_cvt_f64_f32_e32 v[22:23], v10
	v_add_f64 v[2:3], v[2:3], v[22:23]
	v_cvt_f64_f32_e32 v[24:25], v11
	v_add_f64 v[2:3], v[2:3], v[24:25]
	v_cvt_f64_f32_e32 v[18:19], v12
	v_add_f64 v[2:3], v[2:3], v[18:19]
	v_cvt_f64_f32_e32 v[20:21], v13
	v_add_f64 v[2:3], v[2:3], v[20:21]
	v_cvt_f64_f32_e32 v[14:15], v14
	v_add_f64 v[2:3], v[2:3], v[14:15]
	v_cvt_f64_f32_e32 v[16:17], v16
	v_add_f64 v[2:3], v[2:3], v[16:17]
	v_cvt_f64_f32_e32 v[10:11], v70
	v_add_f64 v[2:3], v[2:3], v[10:11]
	v_lshl_add_u32 v70, v184, 3, 0
	v_cvt_f64_f32_e32 v[12:13], v71
	v_add_f64 v[2:3], v[2:3], v[12:13]
	v_cvt_f64_f32_e32 v[6:7], v4
	v_add_f64 v[2:3], v[2:3], v[6:7]
	v_cvt_f64_f32_e32 v[8:9], v5
	v_add_f64 v[4:5], v[2:3], v[8:9]
	v_cvt_f64_f32_e32 v[2:3], v72
	v_add_f64 v[66:67], v[4:5], v[2:3]
	v_cvt_f64_f32_e32 v[4:5], v73
	v_add_f64 v[66:67], v[66:67], v[4:5]
	ds_write_b64 v70, v[66:67]
	s_waitcnt lgkmcnt(0)
	s_barrier
	ds_read_b64 v[68:69], v70
	s_and_saveexec_b64 s[0:1], vcc
	s_cbranch_execz .LBB0_384
	v_add_u32_e32 v71, -8, v70
	ds_read_b64 v[72:73], v71
	s_waitcnt lgkmcnt(0)
	v_add_f64 v[68:69], v[68:69], v[72:73]

; #define LAS __attribute__((address_space(3)))
; __device__ __forceinline__ void norm_phase(ArgP a, LAS unsigned char* lds, int l, bool final_, const int tid, const int bid) {
;     ...
;     const float* xsrc = (l == 0 && !final_) ? a->x : XR;
;     for (int row = bid * NWAVES + wave; row < SEQ; row += gridDim.x * NWAVES) {
;         const f32x4* xr = (const f32x4*)(xsrc + (size_t)row * DM);
;         f32x4 v[8]; float ss = 0.f;
; #pragma unroll
;         for (int j = 0; j < 8; ++j) { v[j] = xr[64 * j + lane]; ss += (v[j][0] * v[j][0] + v[j][1] * v[j][1]) + (v[j][2] * v[j][2] + v[j][3] * v[j][3]); }
;         ss = wave_sum(ss);
;         const float rstd = 1.f / sqrtf(ss * (1.f / DM) + 1e-6f);
;         if (final_) {
;             f32x4* orow = (f32x4*)(a->out + (size_t)row * DM);
; #pragma unroll
;             for (int j = 0; j < 8; ++j) { const f32x4 a1 = ((const LAS f32x4*)A1)[64 * j + lane]; orow[64 * j + lane] = v[j] * rstd * a1; }
;         } else {
;             float fd[8];
; #pragma unroll
;             for (int q = 0; q < 8; ++q) fd[q] = 0.f;
;             u32x2* hrow = (u32x2*)(H + (size_t)row * DM);
.LBB0_525:
	s_lshl_b32 s2, s54, 3
	s_ashr_i32 s3, s12, 6
	s_add_i32 s2, s3, s2
	s_cmpk_gt_i32 s2, 0x3fff
	s_cbranch_scc1 .LBB0_530
	v_and_b32_e32 v0, 63, v184
	v_readlane_b32 s4, v255, 25
	v_readlane_b32 s5, v255, 26
	v_lshlrev_b32_e32 v180, 16, v0
	v_lshl_add_u32 v28, s4, 3, v0
	v_lshl_add_u64 v[2:3], s[72:73], 0, v[180:181]
	s_mov_b64 s[4:5], 0x8700000
	v_lshlrev_b32_e32 v180, 3, v0
	v_lshl_add_u32 v37, v0, 4, 0
	v_lshl_add_u64 v[30:31], v[2:3], 0, s[4:5]
	v_or_b32_e32 v2, 0x100, v0
	v_or_b32_e32 v4, 0x140, v0
	v_or_b32_e32 v6, 0x180, v0
	v_or_b32_e32 v8, 0x1c0, v0
	v_lshl_add_u64 v[10:11], s[72:73], 0, v[180:181]
	s_mov_b64 s[4:5], 0x8a00000
	v_add_u32_e32 v38, 0x4000, v37
	v_cmp_gt_u32_e64 s[6:7], 8, v0
	v_ashrrev_i32_e32 v29, 31, v28
	v_cmp_eq_u32_e64 s[8:9], 7, v0
	v_cmp_eq_u32_e64 s[10:11], 6, v0
	v_cmp_eq_u32_e64 s[12:13], 5, v0
	v_cmp_eq_u32_e64 s[14:15], 4, v0
	v_cmp_eq_u32_e64 s[16:17], 3, v0
	v_cmp_eq_u32_e64 s[18:19], 2, v0
	v_cmp_eq_u32_e64 s[20:21], 1, v0
	v_lshl_add_u64 v[32:33], v[10:11], 0, s[4:5]
	v_lshlrev_b32_e32 v39, 4, v0
	v_lshlrev_b32_e32 v40, 4, v2
	v_lshlrev_b32_e32 v41, 4, v4
	v_lshlrev_b32_e32 v42, 4, v6
	v_lshlrev_b32_e32 v43, 4, v8
	s_branch .LBB0_528

; #define LAS __attribute__((address_space(3)))
; __device__ __forceinline__ unsigned cvt_pk_bf16(float lo, float hi) { unsigned r; asm volatile("v_cvt_pk_bf16_f32 %0, %1, %2" : "=v"(r) : "v"(lo), "v"(hi)); return r; }
; __device__ __forceinline__ void norm_phase(ArgP a, LAS unsigned char* lds, int l, bool final_, const int tid, const int bid) {
;     ...
;     for (int row = bid * NWAVES + wave; row < SEQ; row += gridDim.x * NWAVES) {
;         const f32x4* xr = (const f32x4*)(xsrc + (size_t)row * DM);
;         f32x4 v[8]; float ss = 0.f;
; #pragma unroll
;         for (int j = 0; j < 8; ++j) { v[j] = xr[64 * j + lane]; ss += (v[j][0] * v[j][0] + v[j][1] * v[j][1]) + (v[j][2] * v[j][2] + v[j][3] * v[j][3]); }
;         ss = wave_sum(ss);
;         const float rstd = 1.f / sqrtf(ss * (1.f / DM) + 1e-6f);
;         if (final_) {
;             f32x4* orow = (f32x4*)(a->out + (size_t)row * DM);
; #pragma unroll
;             for (int j = 0; j < 8; ++j) { const f32x4 a1 = ((const LAS f32x4*)A1)[64 * j + lane]; orow[64 * j + lane] = v[j] * rstd * a1; }
;         } else {
;             float fd[8];
; #pragma unroll
;             for (int q = 0; q < 8; ++q) fd[q] = 0.f;
;             u32x2* hrow = (u32x2*)(H + (size_t)row * DM);
; #pragma unroll
;             for (int j = 0; j < 8; ++j) {
;                 const f32x4 a1 = ((const LAS f32x4*)A1)[64 * j + lane], a2 = ((const LAS f32x4*)A2)[64 * j + lane];
;                 const f32x4 h = v[j] * rstd * a1 + a2;
;                 u32x2 w; w.x = cvt_pk_bf16(h[0], h[1]); w.y = cvt_pk_bf16(h[2], h[3]); hrow[64 * j + lane] = w;
; #pragma unroll
;                 for (int q = 0; q < 8; ++q) { const f32x4 wf = ((const LAS f32x4*)WFt)[q * 512 + 64 * j + lane]; fd[q] += (h[0] * wf[0] + h[1] * wf[1]) + (h[2] * wf[2] + h[3] * wf[3]); }
.LBB0_528:
	s_ashr_i32 s3, s2, 31
	s_lshl_b64 s[4:5], s[2:3], 13
	s_waitcnt lgkmcnt(0)
	s_add_u32 s4, s0, s4
	s_addc_u32 s5, s1, s5
	global_load_dwordx4 v[44:47], v39, s[4:5]
	global_load_dwordx4 v[24:27], v39, s[4:5] offset:1024
	global_load_dwordx4 v[20:23], v39, s[4:5] offset:2048
	global_load_dwordx4 v[16:19], v39, s[4:5] offset:3072
	global_load_dwordx4 v[12:15], v40, s[4:5]
	global_load_dwordx4 v[8:11], v41, s[4:5]
	global_load_dwordx4 v[4:7], v42, s[4:5]
	global_load_dwordx4 v[0:3], v43, s[4:5]
	s_lshl_b64 s[4:5], s[2:3], 12
	s_waitcnt vmcnt(7)
	v_mul_f32_e32 v34, v45, v45
	v_mul_f32_e32 v35, v47, v47
	s_waitcnt vmcnt(6)
	v_mul_f32_e32 v36, v25, v25
	v_mul_f32_e32 v48, v27, v27
	s_waitcnt vmcnt(5)
	v_mul_f32_e32 v49, v21, v21
	v_mul_f32_e32 v50, v23, v23
	v_fmac_f32_e32 v34, v44, v44
	v_fmac_f32_e32 v35, v46, v46
	v_fmac_f32_e32 v36, v24, v24
	v_fmac_f32_e32 v48, v26, v26
	s_waitcnt vmcnt(4)
	v_mul_f32_e32 v51, v17, v17
	v_mul_f32_e32 v52, v19, v19
	v_fmac_f32_e32 v49, v20, v20
	v_fmac_f32_e32 v50, v22, v22
	v_add_f32_e32 v34, v34, v35
	v_add_f32_e32 v35, v36, v48
	s_waitcnt vmcnt(3)
	v_mul_f32_e32 v53, v13, v13
	v_mul_f32_e32 v54, v15, v15
	v_fmac_f32_e32 v51, v16, v16
	v_fmac_f32_e32 v52, v18, v18
	v_add_f32_e32 v36, v49, v50
	v_add_f32_e32 v34, v34, v35
	s_waitcnt vmcnt(2)
	v_mul_f32_e32 v55, v9, v9
	v_mul_f32_e32 v56, v11, v11
	v_fmac_f32_e32 v53, v12, v12
	v_fmac_f32_e32 v54, v14, v14
	v_add_f32_e32 v48, v51, v52
	v_add_f32_e32 v34, v34, v36
	s_waitcnt vmcnt(1)
	v_mul_f32_e32 v57, v5, v5
	v_mul_f32_e32 v58, v7, v7
	v_fmac_f32_e32 v55, v8, v8
	v_fmac_f32_e32 v56, v10, v10
	v_add_f32_e32 v49, v53, v54
	v_add_f32_e32 v34, v34, v48
	s_waitcnt vmcnt(0)
	v_mul_f32_e32 v59, v1, v1
	v_mul_f32_e32 v60, v3, v3
	v_fmac_f32_e32 v57, v4, v4
	v_fmac_f32_e32 v58, v6, v6
	v_add_f32_e32 v50, v55, v56
	v_add_f32_e32 v34, v34, v49
	v_fmac_f32_e32 v59, v0, v0
	v_fmac_f32_e32 v60, v2, v2
	v_add_f32_e32 v51, v57, v58
	v_add_f32_e32 v34, v34, v50
	v_add_f32_e32 v52, v59, v60
	v_add_f32_e32 v34, v34, v51
	v_add_f32_e32 v34, v34, v52
	ds_swizzle_b32 v35, v34 offset:swizzle(SWAP,1)
	ds_read_b128 v[48:51], v37
	ds_read_b128 v[52:55], v37 offset:8192
	s_waitcnt lgkmcnt(2)
	v_add_f32_e32 v34, v34, v35
	ds_swizzle_b32 v35, v34 offset:swizzle(SWAP,2)
	s_waitcnt lgkmcnt(0)
	v_add_f32_e32 v34, v34, v35
	ds_swizzle_b32 v35, v34 offset:swizzle(SWAP,4)
	s_waitcnt lgkmcnt(0)
	v_add_f32_e32 v34, v34, v35
	ds_swizzle_b32 v35, v34 offset:swizzle(SWAP,8)
	s_waitcnt lgkmcnt(0)
	v_add_f32_e32 v34, v34, v35
	ds_swizzle_b32 v35, v34 offset:swizzle(SWAP,16)
	s_waitcnt lgkmcnt(0)
	v_add_f32_e32 v34, v34, v35
	v_mov_b32_e32 v35, v34
	s_nop 1
	v_permlane32_swap_b32_e32 v34, v35
	v_add_f32_e32 v34, v34, v35
	v_fmamk_f32 v34, v34, 0x3a000000, v187
	v_mul_f32_e32 v35, 0x4f800000, v34
	v_cmp_gt_f32_e32 vcc, s94, v34
	s_nop 1
	v_cndmask_b32_e32 v34, v34, v35, vcc
	v_sqrt_f32_e32 v35, v34
	s_nop 0
	v_add_u32_e32 v36, -1, v35
	v_add_u32_e32 v56, 1, v35
	v_fma_f32 v57, -v36, v35, v34
	v_fma_f32 v58, -v56, v35, v34
	v_cmp_ge_f32_e64 s[22:23], 0, v57
	s_nop 1
	v_cndmask_b32_e64 v35, v35, v36, s[22:23]
	v_cmp_lt_f32_e64 s[22:23], 0, v58
	s_nop 1
	v_cndmask_b32_e64 v35, v35, v56, s[22:23]
	v_mul_f32_e32 v36, 0x37800000, v35
	v_cndmask_b32_e32 v35, v35, v36, vcc
	v_cmp_class_f32_e32 vcc, v34, v194
	s_nop 1
	v_cndmask_b32_e32 v36, v35, v34, vcc
	v_div_scale_f32 v56, s[22:23], v36, v36, 1.0
	v_rcp_f32_e32 v57, v56
	v_div_scale_f32 v58, vcc, 1.0, v36, 1.0
	v_lshl_add_u64 v[34:35], v[32:33], 0, s[4:5]
	v_fma_f32 v59, -v56, v57, 1.0
	v_fmac_f32_e32 v57, v59, v57
	v_mul_f32_e32 v59, v58, v57
	v_fma_f32 v60, -v56, v59, v58
	v_fmac_f32_e32 v59, v60, v57
	v_fma_f32 v56, -v56, v59, v58
	v_div_fmas_f32 v56, v56, v57, v59
	v_div_fixup_f32 v36, v56, v36, 1.0
	v_pk_mul_f32 v[44:45], v[44:45], v[36:37] op_sel_hi:[1,0]
	v_pk_mul_f32 v[46:47], v[46:47], v[36:37] op_sel_hi:[1,0]
	v_pk_fma_f32 v[78:79], v[48:49], v[44:45], v[52:53]
	v_pk_fma_f32 v[76:77], v[50:51], v[46:47], v[54:55]
	v_cvt_pk_bf16_f32 v80, v78, v79
	v_pk_mul_f32 v[24:25], v[24:25], v[36:37] op_sel_hi:[1,0]
	v_cvt_pk_bf16_f32 v81, v76, v77
	ds_read_b128 v[44:47], v37 offset:16384
	ds_read_b128 v[48:51], v37 offset:24576
	ds_read_b128 v[52:55], v37 offset:32768
	ds_read_b128 v[56:59], v37 offset:40960
	ds_read_b128 v[60:63], v37 offset:49152
	ds_read_b128 v[64:67], v37 offset:57344
	ds_read_b128 v[68:71], v38 offset:49152
	ds_read_b128 v[72:75], v38 offset:57344
	s_waitcnt lgkmcnt(7)
	v_mul_f32_e32 v45, v45, v79
	v_mul_f32_e32 v47, v47, v77
	s_waitcnt lgkmcnt(6)
	v_mul_f32_e32 v49, v49, v79
	v_mul_f32_e32 v51, v51, v77
	s_waitcnt lgkmcnt(5)
	v_mul_f32_e32 v53, v53, v79
	v_mul_f32_e32 v55, v55, v77
	s_waitcnt lgkmcnt(4)
	v_mul_f32_e32 v57, v57, v79
	v_mul_f32_e32 v59, v59, v77
	s_waitcnt lgkmcnt(3)
	v_mul_f32_e32 v61, v61, v79
	v_mul_f32_e32 v63, v63, v77
	s_waitcnt lgkmcnt(2)
	v_mul_f32_e32 v65, v65, v79
	v_mul_f32_e32 v67, v67, v77
	s_waitcnt lgkmcnt(1)
	v_mul_f32_e32 v69, v79, v69
	v_mul_f32_e32 v71, v77, v71
	v_fmac_f32_e32 v45, v44, v78
	v_fmac_f32_e32 v47, v46, v76
	v_fmac_f32_e32 v49, v48, v78
	v_fmac_f32_e32 v51, v50, v76
	v_fmac_f32_e32 v53, v52, v78
	v_fmac_f32_e32 v55, v54, v76
	v_fmac_f32_e32 v57, v56, v78
	v_fmac_f32_e32 v59, v58, v76
	v_fmac_f32_e32 v61, v60, v78
	v_fmac_f32_e32 v63, v62, v76
	v_fmac_f32_e32 v65, v64, v78
	v_fmac_f32_e32 v67, v66, v76
	v_fmac_f32_e32 v69, v78, v68
	v_fmac_f32_e32 v71, v76, v70
	global_store_dwordx2 v[34:35], v[80:81], off
	v_add_f32_e32 v44, v45, v47
	v_add_f32_e32 v45, v49, v51
	v_add_f32_e32 v46, v53, v55
	v_add_f32_e32 v47, v57, v59
	v_add_f32_e32 v48, v61, v63
	v_add_f32_e32 v49, v65, v67
	v_add_f32_e32 v50, v69, v71
	v_add_f32_e32 v54, 0, v44
	v_add_f32_e32 v55, 0, v45
	v_add_f32_e32 v56, 0, v46
	v_add_f32_e32 v57, 0, v47
	v_add_f32_e32 v58, 0, v48
	v_add_f32_e32 v59, 0, v49
	v_add_f32_e32 v60, 0, v50
	ds_read_b128 v[44:47], v37 offset:1024
	ds_read_b128 v[48:51], v37 offset:9216
	v_pk_mul_f32 v[26:27], v[26:27], v[36:37] op_sel_hi:[1,0]
	s_waitcnt lgkmcnt(2)
; #define LAS __attribute__((address_space(3)))
; __device__ __forceinline__ unsigned cvt_pk_bf16(float lo, float hi) { unsigned r; asm volatile("v_cvt_pk_bf16_f32 %0, %1, %2" : "=v"(r) : "v"(lo), "v"(hi)); return r; }
; __device__ __forceinline__ void norm_phase(ArgP a, LAS unsigned char* lds, int l, bool final_, const int tid, const int bid) {
;     ...
; #pragma unroll
;             for (int j = 0; j < 8; ++j) {
;                 const f32x4 a1 = ((const LAS f32x4*)A1)[64 * j + lane], a2 = ((const LAS f32x4*)A2)[64 * j + lane];
;                 const f32x4 h = v[j] * rstd * a1 + a2;
;                 u32x2 w; w.x = cvt_pk_bf16(h[0], h[1]); w.y = cvt_pk_bf16(h[2], h[3]); hrow[64 * j + lane] = w;
; #pragma unroll
;                 for (int q = 0; q < 8; ++q) { const f32x4 wf = ((const LAS f32x4*)WFt)[q * 512 + 64 * j + lane]; fd[q] += (h[0] * wf[0] + h[1] * wf[1]) + (h[2] * wf[2] + h[3] * wf[3]); }
;             }
	v_mul_f32_e32 v61, v79, v73
	v_mul_f32_e32 v62, v77, v75
	v_fmac_f32_e32 v61, v78, v72
	s_waitcnt lgkmcnt(0)
	v_pk_fma_f32 v[52:53], v[26:27], v[46:47], v[50:51]
	v_pk_fma_f32 v[48:49], v[24:25], v[44:45], v[48:49]
	v_fmac_f32_e32 v62, v76, v74
	v_cvt_pk_bf16_f32 v44, v48, v49
	v_cvt_pk_bf16_f32 v45, v52, v53
	ds_read_b128 v[24:27], v37 offset:17408
	v_add_f32_e32 v46, v61, v62
	v_add_f32_e32 v61, 0, v46
	global_store_dwordx2 v[34:35], v[44:45], off offset:512
	ds_read_b128 v[44:47], v37 offset:25600
	s_waitcnt lgkmcnt(1)
	v_mul_f32_e32 v25, v49, v25
	v_fmac_f32_e32 v25, v48, v24
	v_mul_f32_e32 v24, v53, v27
	v_fmac_f32_e32 v24, v52, v26
	v_add_f32_e32 v24, v25, v24
	s_waitcnt lgkmcnt(0)
	v_mul_f32_e32 v45, v49, v45
	v_add_f32_e32 v54, v54, v24
	v_fmac_f32_e32 v45, v48, v44
	v_mul_f32_e32 v44, v53, v47
	ds_read_b128 v[24:27], v37 offset:33792
	v_fmac_f32_e32 v44, v52, v46
	v_add_f32_e32 v44, v45, v44
	v_add_f32_e32 v55, v55, v44
	ds_read_b128 v[44:47], v37 offset:41984
	s_waitcnt lgkmcnt(1)
	v_mul_f32_e32 v25, v49, v25
	v_fmac_f32_e32 v25, v48, v24
	v_mul_f32_e32 v24, v53, v27
	v_fmac_f32_e32 v24, v52, v26
	v_add_f32_e32 v24, v25, v24
	s_waitcnt lgkmcnt(0)
	v_mul_f32_e32 v45, v49, v45
	v_add_f32_e32 v56, v56, v24
	v_fmac_f32_e32 v45, v48, v44
	v_mul_f32_e32 v44, v53, v47
	ds_read_b128 v[24:27], v37 offset:50176
	v_fmac_f32_e32 v44, v52, v46
	v_add_f32_e32 v44, v45, v44
	v_add_f32_e32 v57, v57, v44
	ds_read_b128 v[44:47], v37 offset:58368
	s_waitcnt lgkmcnt(1)
	v_mul_f32_e32 v25, v49, v25
	v_fmac_f32_e32 v25, v48, v24
	v_mul_f32_e32 v24, v53, v27
	v_fmac_f32_e32 v24, v52, v26
	v_add_f32_e32 v24, v25, v24
	s_waitcnt lgkmcnt(0)
	v_mul_f32_e32 v45, v49, v45
	v_add_f32_e32 v58, v58, v24
	v_fmac_f32_e32 v45, v48, v44
	v_mul_f32_e32 v44, v53, v47
	ds_read_b128 v[24:27], v38 offset:50176
	v_fmac_f32_e32 v44, v52, v46
	v_add_f32_e32 v44, v45, v44
	v_add_f32_e32 v59, v59, v44
	ds_read_b128 v[44:47], v38 offset:58368
	s_waitcnt lgkmcnt(1)
	v_mul_f32_e32 v25, v49, v25
	v_fmac_f32_e32 v25, v48, v24
	v_mul_f32_e32 v24, v53, v27
	v_fmac_f32_e32 v24, v52, v26
	v_add_f32_e32 v24, v25, v24
	s_waitcnt lgkmcnt(0)
	v_mul_f32_e32 v62, v49, v45
	v_add_f32_e32 v60, v60, v24
	v_fmac_f32_e32 v62, v48, v44
	ds_read_b128 v[24:27], v37 offset:2048
	ds_read_b128 v[48:51], v37 offset:10240
	v_pk_mul_f32 v[20:21], v[20:21], v[36:37] op_sel_hi:[1,0]
	v_pk_mul_f32 v[22:23], v[22:23], v[36:37] op_sel_hi:[1,0]
	v_mul_f32_e32 v47, v53, v47
	v_fmac_f32_e32 v47, v52, v46
	s_waitcnt lgkmcnt(0)
	v_pk_fma_f32 v[50:51], v[22:23], v[26:27], v[50:51]
	v_pk_fma_f32 v[44:45], v[20:21], v[24:25], v[48:49]
	v_add_f32_e32 v26, v62, v47
	v_cvt_pk_bf16_f32 v24, v44, v45
	v_cvt_pk_bf16_f32 v25, v50, v51
	ds_read_b128 v[20:23], v37 offset:18432
	v_add_f32_e32 v48, v61, v26
	global_store_dwordx2 v[34:35], v[24:25], off offset:1024
	ds_read_b128 v[24:27], v37 offset:26624
	v_pk_mul_f32 v[16:17], v[16:17], v[36:37] op_sel_hi:[1,0]
	s_waitcnt lgkmcnt(1)
	v_mul_f32_e32 v21, v45, v21
	v_fmac_f32_e32 v21, v44, v20
	v_mul_f32_e32 v20, v51, v23
	v_fmac_f32_e32 v20, v50, v22
	v_add_f32_e32 v20, v21, v20
	s_waitcnt lgkmcnt(0)
	v_mul_f32_e32 v25, v45, v25
	v_add_f32_e32 v49, v54, v20
	v_fmac_f32_e32 v25, v44, v24
	v_mul_f32_e32 v24, v51, v27
	ds_read_b128 v[20:23], v37 offset:34816
	v_fmac_f32_e32 v24, v50, v26
	v_add_f32_e32 v24, v25, v24
	v_add_f32_e32 v52, v55, v24
	ds_read_b128 v[24:27], v37 offset:43008
	s_waitcnt lgkmcnt(1)
	v_mul_f32_e32 v21, v45, v21
	v_fmac_f32_e32 v21, v44, v20
	v_mul_f32_e32 v20, v51, v23
	v_fmac_f32_e32 v20, v50, v22
	v_add_f32_e32 v20, v21, v20
	s_waitcnt lgkmcnt(0)
	v_mul_f32_e32 v25, v45, v25
	v_add_f32_e32 v53, v56, v20
	v_fmac_f32_e32 v25, v44, v24
	v_mul_f32_e32 v24, v51, v27
	ds_read_b128 v[20:23], v37 offset:51200
	v_fmac_f32_e32 v24, v50, v26
	v_add_f32_e32 v24, v25, v24
	v_add_f32_e32 v54, v57, v24
	ds_read_b128 v[24:27], v37 offset:59392
	s_waitcnt lgkmcnt(1)
	v_mul_f32_e32 v21, v45, v21
	v_fmac_f32_e32 v21, v44, v20
	v_mul_f32_e32 v20, v51, v23
	v_fmac_f32_e32 v20, v50, v22
	v_add_f32_e32 v20, v21, v20
	s_waitcnt lgkmcnt(0)
	v_mul_f32_e32 v25, v45, v25
	v_add_f32_e32 v55, v58, v20
	v_fmac_f32_e32 v25, v44, v24
	v_mul_f32_e32 v24, v51, v27
	ds_read_b128 v[20:23], v38 offset:51200
	v_fmac_f32_e32 v24, v50, v26
	v_add_f32_e32 v24, v25, v24
	v_add_f32_e32 v56, v59, v24
	ds_read_b128 v[24:27], v38 offset:59392
	s_waitcnt lgkmcnt(1)
	v_mul_f32_e32 v21, v45, v21
	v_fmac_f32_e32 v21, v44, v20
	v_mul_f32_e32 v20, v51, v23
	v_fmac_f32_e32 v20, v50, v22
	v_add_f32_e32 v20, v21, v20
	s_waitcnt lgkmcnt(0)
	v_mul_f32_e32 v58, v45, v25
	v_add_f32_e32 v57, v60, v20
	v_fmac_f32_e32 v58, v44, v24
	ds_read_b128 v[20:23], v37 offset:3072
	ds_read_b128 v[44:47], v37 offset:11264
	v_pk_mul_f32 v[18:19], v[18:19], v[36:37] op_sel_hi:[1,0]
	v_mul_f32_e32 v27, v51, v27
	v_fmac_f32_e32 v27, v50, v26
	v_pk_mul_f32 v[12:13], v[12:13], v[36:37] op_sel_hi:[1,0]
	s_waitcnt lgkmcnt(0)
	v_pk_fma_f32 v[46:47], v[18:19], v[22:23], v[46:47]
	v_pk_fma_f32 v[24:25], v[16:17], v[20:21], v[44:45]
	v_add_f32_e32 v22, v58, v27
	v_cvt_pk_bf16_f32 v20, v24, v25
	v_cvt_pk_bf16_f32 v21, v46, v47
	ds_read_b128 v[16:19], v37 offset:19456
	v_add_f32_e32 v44, v48, v22
	global_store_dwordx2 v[34:35], v[20:21], off offset:1536
	ds_read_b128 v[20:23], v37 offset:27648
	v_pk_mul_f32 v[14:15], v[14:15], v[36:37] op_sel_hi:[1,0]
	s_waitcnt lgkmcnt(1)
	v_mul_f32_e32 v17, v25, v17
	v_fmac_f32_e32 v17, v24, v16
	v_mul_f32_e32 v16, v47, v19
	v_fmac_f32_e32 v16, v46, v18
	v_add_f32_e32 v16, v17, v16
	s_waitcnt lgkmcnt(0)
; #define LAS __attribute__((address_space(3)))
; __device__ __forceinline__ unsigned cvt_pk_bf16(float lo, float hi) { unsigned r; asm volatile("v_cvt_pk_bf16_f32 %0, %1, %2" : "=v"(r) : "v"(lo), "v"(hi)); return r; }
; __device__ __forceinline__ void norm_phase(ArgP a, LAS unsigned char* lds, int l, bool final_, const int tid, const int bid) {
;     ...
; #pragma unroll
;             for (int j = 0; j < 8; ++j) {
;                 const f32x4 a1 = ((const LAS f32x4*)A1)[64 * j + lane], a2 = ((const LAS f32x4*)A2)[64 * j + lane];
;                 const f32x4 h = v[j] * rstd * a1 + a2;
;                 u32x2 w; w.x = cvt_pk_bf16(h[0], h[1]); w.y = cvt_pk_bf16(h[2], h[3]); hrow[64 * j + lane] = w;
; #pragma unroll
;                 for (int q = 0; q < 8; ++q) { const f32x4 wf = ((const LAS f32x4*)WFt)[q * 512 + 64 * j + lane]; fd[q] += (h[0] * wf[0] + h[1] * wf[1]) + (h[2] * wf[2] + h[3] * wf[3]); }
;             }
	v_mul_f32_e32 v21, v25, v21
	v_add_f32_e32 v45, v49, v16
	v_fmac_f32_e32 v21, v24, v20
	v_mul_f32_e32 v20, v47, v23
	ds_read_b128 v[16:19], v37 offset:35840
	v_fmac_f32_e32 v20, v46, v22
	v_add_f32_e32 v20, v21, v20
	v_add_f32_e32 v48, v52, v20
	ds_read_b128 v[20:23], v37 offset:44032
	s_waitcnt lgkmcnt(1)
	v_mul_f32_e32 v17, v25, v17
	v_fmac_f32_e32 v17, v24, v16
	v_mul_f32_e32 v16, v47, v19
	v_fmac_f32_e32 v16, v46, v18
	v_add_f32_e32 v16, v17, v16
	s_waitcnt lgkmcnt(0)
	v_mul_f32_e32 v21, v25, v21
	v_add_f32_e32 v49, v53, v16
	v_fmac_f32_e32 v21, v24, v20
	v_mul_f32_e32 v20, v47, v23
	ds_read_b128 v[16:19], v37 offset:52224
	v_fmac_f32_e32 v20, v46, v22
	v_add_f32_e32 v20, v21, v20
	v_add_f32_e32 v50, v54, v20
	ds_read_b128 v[20:23], v37 offset:60416
	s_waitcnt lgkmcnt(1)
	v_mul_f32_e32 v17, v25, v17
	v_fmac_f32_e32 v17, v24, v16
	v_mul_f32_e32 v16, v47, v19
	v_fmac_f32_e32 v16, v46, v18
	v_add_f32_e32 v16, v17, v16
	s_waitcnt lgkmcnt(0)
	v_mul_f32_e32 v21, v25, v21
	v_add_f32_e32 v51, v55, v16
	v_fmac_f32_e32 v21, v24, v20
	v_mul_f32_e32 v20, v47, v23
	ds_read_b128 v[16:19], v38 offset:52224
	v_fmac_f32_e32 v20, v46, v22
	v_add_f32_e32 v20, v21, v20
	v_add_f32_e32 v52, v56, v20
	ds_read_b128 v[20:23], v38 offset:60416
	s_waitcnt lgkmcnt(1)
	v_mul_f32_e32 v17, v25, v17
	v_fmac_f32_e32 v17, v24, v16
	v_mul_f32_e32 v16, v47, v19
	v_fmac_f32_e32 v16, v46, v18
	v_add_f32_e32 v16, v17, v16
	s_waitcnt lgkmcnt(0)
	v_mul_f32_e32 v54, v25, v21
	v_add_f32_e32 v53, v57, v16
	v_fmac_f32_e32 v54, v24, v20
	ds_read_b128 v[16:19], v37 offset:4096
	ds_read_b128 v[24:27], v37 offset:12288
	v_mul_f32_e32 v23, v47, v23
	v_fmac_f32_e32 v23, v46, v22
	v_pk_mul_f32 v[8:9], v[8:9], v[36:37] op_sel_hi:[1,0]
	v_pk_mul_f32 v[10:11], v[10:11], v[36:37] op_sel_hi:[1,0]
	s_waitcnt lgkmcnt(0)
	v_pk_fma_f32 v[26:27], v[14:15], v[18:19], v[26:27]
	v_pk_fma_f32 v[20:21], v[12:13], v[16:17], v[24:25]
	v_add_f32_e32 v18, v54, v23
	v_cvt_pk_bf16_f32 v16, v20, v21
	v_cvt_pk_bf16_f32 v17, v26, v27
	ds_read_b128 v[12:15], v37 offset:20480
	v_add_f32_e32 v24, v44, v18
	global_store_dwordx2 v[34:35], v[16:17], off offset:2048
	ds_read_b128 v[16:19], v37 offset:28672
	v_pk_mul_f32 v[4:5], v[4:5], v[36:37] op_sel_hi:[1,0]
	s_waitcnt lgkmcnt(1)
	v_mul_f32_e32 v13, v21, v13
	v_fmac_f32_e32 v13, v20, v12
	v_mul_f32_e32 v12, v27, v15
	v_fmac_f32_e32 v12, v26, v14
	v_add_f32_e32 v12, v13, v12
	s_waitcnt lgkmcnt(0)
	v_mul_f32_e32 v17, v21, v17
	v_add_f32_e32 v25, v45, v12
	v_fmac_f32_e32 v17, v20, v16
	v_mul_f32_e32 v16, v27, v19
	ds_read_b128 v[12:15], v37 offset:36864
	v_fmac_f32_e32 v16, v26, v18
	v_add_f32_e32 v16, v17, v16
	v_add_f32_e32 v44, v48, v16
	ds_read_b128 v[16:19], v37 offset:45056
	s_waitcnt lgkmcnt(1)
	v_mul_f32_e32 v13, v21, v13
	v_fmac_f32_e32 v13, v20, v12
	v_mul_f32_e32 v12, v27, v15
	v_fmac_f32_e32 v12, v26, v14
	v_add_f32_e32 v12, v13, v12
	s_waitcnt lgkmcnt(0)
	v_mul_f32_e32 v17, v21, v17
	v_add_f32_e32 v45, v49, v12
	v_fmac_f32_e32 v17, v20, v16
	v_mul_f32_e32 v16, v27, v19
	ds_read_b128 v[12:15], v37 offset:53248
	v_fmac_f32_e32 v16, v26, v18
	v_add_f32_e32 v16, v17, v16
	v_add_f32_e32 v46, v50, v16
	ds_read_b128 v[16:19], v37 offset:61440
	s_waitcnt lgkmcnt(1)
	v_mul_f32_e32 v13, v21, v13
	v_fmac_f32_e32 v13, v20, v12
	v_mul_f32_e32 v12, v27, v15
	v_fmac_f32_e32 v12, v26, v14
	v_add_f32_e32 v12, v13, v12
	s_waitcnt lgkmcnt(0)
	v_mul_f32_e32 v17, v21, v17
	v_add_f32_e32 v47, v51, v12
	v_fmac_f32_e32 v17, v20, v16
	v_mul_f32_e32 v16, v27, v19
	ds_read_b128 v[12:15], v38 offset:53248
	v_fmac_f32_e32 v16, v26, v18
	v_add_f32_e32 v16, v17, v16
	v_add_f32_e32 v48, v52, v16
	ds_read_b128 v[16:19], v38 offset:61440
	s_waitcnt lgkmcnt(1)
	v_mul_f32_e32 v13, v21, v13
	v_fmac_f32_e32 v13, v20, v12
	v_mul_f32_e32 v12, v27, v15
	v_fmac_f32_e32 v12, v26, v14
	v_add_f32_e32 v12, v13, v12
	s_waitcnt lgkmcnt(0)
	v_mul_f32_e32 v50, v21, v17
	v_add_f32_e32 v49, v53, v12
	v_fmac_f32_e32 v50, v20, v16
	ds_read_b128 v[12:15], v37 offset:5120
	ds_read_b128 v[20:23], v37 offset:13312
	v_mul_f32_e32 v19, v27, v19
	v_fmac_f32_e32 v19, v26, v18
	v_pk_mul_f32 v[6:7], v[6:7], v[36:37] op_sel_hi:[1,0]
	v_pk_mul_f32 v[0:1], v[0:1], v[36:37] op_sel_hi:[1,0]
	s_waitcnt lgkmcnt(0)
	v_pk_fma_f32 v[22:23], v[10:11], v[14:15], v[22:23]
	v_pk_fma_f32 v[16:17], v[8:9], v[12:13], v[20:21]
	v_add_f32_e32 v14, v50, v19
	v_cvt_pk_bf16_f32 v12, v16, v17
	v_cvt_pk_bf16_f32 v13, v22, v23
	ds_read_b128 v[8:11], v37 offset:21504
	v_add_f32_e32 v20, v24, v14
	global_store_dwordx2 v[34:35], v[12:13], off offset:2560
	ds_read_b128 v[12:15], v37 offset:29696
	v_pk_mul_f32 v[2:3], v[2:3], v[36:37] op_sel_hi:[1,0]
	s_waitcnt lgkmcnt(1)
	v_mul_f32_e32 v9, v17, v9
	v_fmac_f32_e32 v9, v16, v8
	v_mul_f32_e32 v8, v23, v11
	v_fmac_f32_e32 v8, v22, v10
	v_add_f32_e32 v8, v9, v8
	s_waitcnt lgkmcnt(0)
	v_mul_f32_e32 v13, v17, v13
	v_add_f32_e32 v21, v25, v8
	v_fmac_f32_e32 v13, v16, v12
	v_mul_f32_e32 v12, v23, v15
	ds_read_b128 v[8:11], v37 offset:37888
	v_fmac_f32_e32 v12, v22, v14
	v_add_f32_e32 v12, v13, v12
	v_add_f32_e32 v24, v44, v12
	ds_read_b128 v[12:15], v37 offset:46080
	s_waitcnt lgkmcnt(1)
	v_mul_f32_e32 v9, v17, v9
	v_fmac_f32_e32 v9, v16, v8
	v_mul_f32_e32 v8, v23, v11
	v_fmac_f32_e32 v8, v22, v10
	v_add_f32_e32 v8, v9, v8
	s_waitcnt lgkmcnt(0)
	v_mul_f32_e32 v13, v17, v13
	v_add_f32_e32 v25, v45, v8
	v_fmac_f32_e32 v13, v16, v12
	v_mul_f32_e32 v12, v23, v15
	ds_read_b128 v[8:11], v37 offset:54272
	v_fmac_f32_e32 v12, v22, v14
	v_add_f32_e32 v12, v13, v12
	v_add_f32_e32 v26, v46, v12
	ds_read_b128 v[12:15], v37 offset:62464
	s_waitcnt lgkmcnt(1)
; #define LAS __attribute__((address_space(3)))
; __device__ __forceinline__ unsigned cvt_pk_bf16(float lo, float hi) { unsigned r; asm volatile("v_cvt_pk_bf16_f32 %0, %1, %2" : "=v"(r) : "v"(lo), "v"(hi)); return r; }
; __device__ __forceinline__ void norm_phase(ArgP a, LAS unsigned char* lds, int l, bool final_, const int tid, const int bid) {
;     ...
; #pragma unroll
;             for (int j = 0; j < 8; ++j) {
;                 const f32x4 a1 = ((const LAS f32x4*)A1)[64 * j + lane], a2 = ((const LAS f32x4*)A2)[64 * j + lane];
;                 const f32x4 h = v[j] * rstd * a1 + a2;
;                 u32x2 w; w.x = cvt_pk_bf16(h[0], h[1]); w.y = cvt_pk_bf16(h[2], h[3]); hrow[64 * j + lane] = w;
; #pragma unroll
;                 for (int q = 0; q < 8; ++q) { const f32x4 wf = ((const LAS f32x4*)WFt)[q * 512 + 64 * j + lane]; fd[q] += (h[0] * wf[0] + h[1] * wf[1]) + (h[2] * wf[2] + h[3] * wf[3]); }
;             }
; #pragma unroll
;             for (int q = 0; q < 8; ++q) fd[q] = wave_sum(fd[q]);
	v_mul_f32_e32 v9, v17, v9
	v_fmac_f32_e32 v9, v16, v8
	v_mul_f32_e32 v8, v23, v11
	v_fmac_f32_e32 v8, v22, v10
	v_add_f32_e32 v8, v9, v8
	s_waitcnt lgkmcnt(0)
	v_mul_f32_e32 v13, v17, v13
	v_add_f32_e32 v27, v47, v8
	v_fmac_f32_e32 v13, v16, v12
	v_mul_f32_e32 v12, v23, v15
	ds_read_b128 v[8:11], v38 offset:54272
	v_fmac_f32_e32 v12, v22, v14
	v_add_f32_e32 v12, v13, v12
	v_add_f32_e32 v44, v48, v12
	ds_read_b128 v[12:15], v38 offset:62464
	s_waitcnt lgkmcnt(1)
	v_mul_f32_e32 v9, v17, v9
	v_fmac_f32_e32 v9, v16, v8
	v_mul_f32_e32 v8, v23, v11
	v_fmac_f32_e32 v8, v22, v10
	v_add_f32_e32 v8, v9, v8
	s_waitcnt lgkmcnt(0)
	v_mul_f32_e32 v46, v17, v13
	v_add_f32_e32 v45, v49, v8
	v_fmac_f32_e32 v46, v16, v12
	ds_read_b128 v[8:11], v37 offset:6144
	ds_read_b128 v[16:19], v37 offset:14336
	v_mul_f32_e32 v15, v23, v15
	v_fmac_f32_e32 v15, v22, v14
	s_waitcnt lgkmcnt(0)
	v_pk_fma_f32 v[18:19], v[6:7], v[10:11], v[18:19]
	v_pk_fma_f32 v[12:13], v[4:5], v[8:9], v[16:17]
	v_add_f32_e32 v10, v46, v15
	v_cvt_pk_bf16_f32 v8, v12, v13
	v_cvt_pk_bf16_f32 v9, v18, v19
	ds_read_b128 v[4:7], v37 offset:22528
	v_add_f32_e32 v16, v20, v10
	global_store_dwordx2 v[34:35], v[8:9], off offset:3072
	ds_read_b128 v[8:11], v37 offset:30720
	s_waitcnt lgkmcnt(1)
	v_mul_f32_e32 v5, v13, v5
	v_fmac_f32_e32 v5, v12, v4
	v_mul_f32_e32 v4, v19, v7
	v_fmac_f32_e32 v4, v18, v6
	v_add_f32_e32 v4, v5, v4
	s_waitcnt lgkmcnt(0)
	v_mul_f32_e32 v9, v13, v9
	v_add_f32_e32 v17, v21, v4
	v_fmac_f32_e32 v9, v12, v8
	v_mul_f32_e32 v8, v19, v11
	ds_read_b128 v[4:7], v37 offset:38912
	v_fmac_f32_e32 v8, v18, v10
	v_add_f32_e32 v8, v9, v8
	v_add_f32_e32 v20, v24, v8
	ds_read_b128 v[8:11], v37 offset:47104
	s_waitcnt lgkmcnt(1)
	v_mul_f32_e32 v5, v13, v5
	v_fmac_f32_e32 v5, v12, v4
	v_mul_f32_e32 v4, v19, v7
	v_fmac_f32_e32 v4, v18, v6
	v_add_f32_e32 v4, v5, v4
	s_waitcnt lgkmcnt(0)
	v_mul_f32_e32 v9, v13, v9
	v_add_f32_e32 v21, v25, v4
	v_fmac_f32_e32 v9, v12, v8
	v_mul_f32_e32 v8, v19, v11
	ds_read_b128 v[4:7], v37 offset:55296
	v_fmac_f32_e32 v8, v18, v10
	v_add_f32_e32 v8, v9, v8
	v_add_f32_e32 v22, v26, v8
	ds_read_b128 v[8:11], v37 offset:63488
	s_waitcnt lgkmcnt(1)
	v_mul_f32_e32 v5, v13, v5
	v_fmac_f32_e32 v5, v12, v4
	v_mul_f32_e32 v4, v19, v7
	v_fmac_f32_e32 v4, v18, v6
	v_add_f32_e32 v4, v5, v4
	s_waitcnt lgkmcnt(0)
	v_mul_f32_e32 v9, v13, v9
	v_add_f32_e32 v23, v27, v4
	v_fmac_f32_e32 v9, v12, v8
	v_mul_f32_e32 v8, v19, v11
	ds_read_b128 v[4:7], v38 offset:55296
	v_fmac_f32_e32 v8, v18, v10
	v_add_f32_e32 v8, v9, v8
	v_add_f32_e32 v24, v44, v8
	ds_read_b128 v[8:11], v38 offset:63488
	s_waitcnt lgkmcnt(1)
	v_mul_f32_e32 v5, v13, v5
	v_fmac_f32_e32 v5, v12, v4
	v_mul_f32_e32 v4, v19, v7
	v_fmac_f32_e32 v4, v18, v6
	v_add_f32_e32 v4, v5, v4
	s_waitcnt lgkmcnt(0)
	v_mul_f32_e32 v26, v13, v9
	v_add_f32_e32 v25, v45, v4
	v_fmac_f32_e32 v26, v12, v8
	ds_read_b128 v[4:7], v37 offset:7168
	ds_read_b128 v[12:15], v37 offset:15360
	v_mul_f32_e32 v19, v19, v11
	v_fmac_f32_e32 v19, v18, v10
	s_waitcnt lgkmcnt(0)
	v_pk_fma_f32 v[8:9], v[2:3], v[6:7], v[14:15]
	v_pk_fma_f32 v[10:11], v[0:1], v[4:5], v[12:13]
	v_add_f32_e32 v6, v26, v19
	v_cvt_pk_bf16_f32 v4, v10, v11
	v_cvt_pk_bf16_f32 v5, v8, v9
	ds_read_b128 v[0:3], v37 offset:23552
	v_add_f32_e32 v12, v16, v6
	global_store_dwordx2 v[34:35], v[4:5], off offset:3584
	ds_read_b128 v[4:7], v37 offset:31744
	s_waitcnt lgkmcnt(1)
	v_mul_f32_e32 v1, v11, v1
	v_fmac_f32_e32 v1, v10, v0
	v_mul_f32_e32 v0, v9, v3
	v_fmac_f32_e32 v0, v8, v2
	v_add_f32_e32 v0, v1, v0
	v_add_f32_e32 v13, v17, v0
	ds_read_b128 v[0:3], v37 offset:39936
	s_waitcnt lgkmcnt(1)
	v_mul_f32_e32 v5, v11, v5
	v_fmac_f32_e32 v5, v10, v4
	v_mul_f32_e32 v4, v9, v7
	v_fmac_f32_e32 v4, v8, v6
	v_add_f32_e32 v4, v5, v4
	v_add_f32_e32 v14, v20, v4
	ds_read_b128 v[4:7], v37 offset:48128
	s_waitcnt lgkmcnt(1)
	v_mul_f32_e32 v1, v11, v1
	v_fmac_f32_e32 v1, v10, v0
	v_mul_f32_e32 v0, v9, v3
	v_fmac_f32_e32 v0, v8, v2
	v_add_f32_e32 v0, v1, v0
	v_add_f32_e32 v15, v21, v0
	ds_read_b128 v[0:3], v37 offset:56320
	s_waitcnt lgkmcnt(1)
	v_mul_f32_e32 v5, v11, v5
	v_fmac_f32_e32 v5, v10, v4
	v_mul_f32_e32 v4, v9, v7
	v_fmac_f32_e32 v4, v8, v6
	v_add_f32_e32 v4, v5, v4
	v_add_f32_e32 v16, v22, v4
	ds_read_b128 v[4:7], v37 offset:64512
	s_waitcnt lgkmcnt(1)
	v_mul_f32_e32 v1, v11, v1
	v_fmac_f32_e32 v1, v10, v0
	v_mul_f32_e32 v0, v9, v3
	v_fmac_f32_e32 v0, v8, v2
	v_add_f32_e32 v0, v1, v0
	v_add_f32_e32 v17, v23, v0
	ds_read_b128 v[0:3], v38 offset:56320
	s_waitcnt lgkmcnt(1)
	v_mul_f32_e32 v5, v11, v5
	v_fmac_f32_e32 v5, v10, v4
	v_mul_f32_e32 v4, v9, v7
	ds_swizzle_b32 v19, v13 offset:swizzle(SWAP,1)
	v_fmac_f32_e32 v4, v8, v6
	v_add_f32_e32 v4, v5, v4
	v_add_f32_e32 v18, v24, v4
	ds_read_b128 v[4:7], v38 offset:64512
	s_waitcnt lgkmcnt(2)
	v_mul_f32_e32 v1, v11, v1
	v_fmac_f32_e32 v1, v10, v0
	v_mul_f32_e32 v0, v9, v3
	v_fmac_f32_e32 v0, v8, v2
	s_waitcnt lgkmcnt(1)
	v_add_f32_e32 v2, v13, v19
	ds_swizzle_b32 v3, v2 offset:swizzle(SWAP,2)
	v_add_f32_e32 v0, v1, v0
	ds_swizzle_b32 v1, v14 offset:swizzle(SWAP,1)
	v_add_f32_e32 v13, v25, v0
	s_waitcnt lgkmcnt(2)
	v_mul_f32_e32 v0, v11, v5
	s_waitcnt lgkmcnt(1)
	v_add_f32_e32 v2, v2, v3
	ds_swizzle_b32 v3, v2 offset:swizzle(SWAP,4)
	s_waitcnt lgkmcnt(1)
	v_add_f32_e32 v1, v14, v1
	ds_swizzle_b32 v5, v1 offset:swizzle(SWAP,2)
	ds_swizzle_b32 v11, v18 offset:swizzle(SWAP,1)
	v_fmac_f32_e32 v0, v10, v4
	s_waitcnt lgkmcnt(2)
	v_add_f32_e32 v2, v2, v3
	ds_swizzle_b32 v3, v2 offset:swizzle(SWAP,8)
	s_waitcnt lgkmcnt(2)
	v_add_f32_e32 v1, v1, v5
	ds_swizzle_b32 v5, v1 offset:swizzle(SWAP,4)
	v_mul_f32_e32 v4, v9, v7
	v_fmac_f32_e32 v4, v8, v6
	v_add_f32_e32 v0, v0, v4
	s_waitcnt lgkmcnt(2)
; __device__ __forceinline__ float wave_sum(float v) {
;     v += lane_xor<1>(v); v += lane_xor<2>(v); v += lane_xor<4>(v); v += lane_xor<8>(v); v += lane_xor<16>(v);
;     { auto rr = __builtin_amdgcn_permlane32_swap(__float_as_uint(v), __float_as_uint(v), false, false); v = __uint_as_float(rr[0]) + __uint_as_float(rr[1]); }
;     return v;
; __device__ __forceinline__ void norm_phase(ArgP a, LAS unsigned char* lds, int l, bool final_, const int tid, const int bid) {
;     ...
;             for (int q = 0; q < 8; ++q) fd[q] = wave_sum(fd[q]);
	v_add_f32_e32 v11, v18, v11
	s_waitcnt lgkmcnt(1)
	v_add_f32_e32 v2, v2, v3
	s_waitcnt lgkmcnt(0)
	v_add_f32_e32 v4, v1, v5
	v_add_f32_e32 v10, v12, v0
	ds_swizzle_b32 v12, v11 offset:swizzle(SWAP,2)
	ds_swizzle_b32 v3, v2 offset:swizzle(SWAP,16)
	ds_swizzle_b32 v5, v4 offset:swizzle(SWAP,8)
	ds_swizzle_b32 v6, v15 offset:swizzle(SWAP,1)
	ds_swizzle_b32 v8, v17 offset:swizzle(SWAP,1)
	s_waitcnt lgkmcnt(4)
	v_add_f32_e32 v11, v11, v12
	s_waitcnt lgkmcnt(3)
	v_add_f32_e32 v0, v2, v3
	s_waitcnt lgkmcnt(2)
	v_add_f32_e32 v2, v4, v5
	s_waitcnt lgkmcnt(1)
	v_add_f32_e32 v4, v15, v6
	ds_swizzle_b32 v6, v16 offset:swizzle(SWAP,1)
	ds_swizzle_b32 v12, v13 offset:swizzle(SWAP,1)
	ds_swizzle_b32 v14, v11 offset:swizzle(SWAP,4)
	ds_swizzle_b32 v15, v10 offset:swizzle(SWAP,1)
	s_waitcnt lgkmcnt(4)
	v_add_f32_e32 v8, v17, v8
	s_waitcnt lgkmcnt(3)
	v_add_f32_e32 v6, v16, v6
	s_waitcnt lgkmcnt(2)
	v_add_f32_e32 v12, v13, v12
	s_waitcnt lgkmcnt(1)
	v_add_f32_e32 v11, v11, v14
	s_waitcnt lgkmcnt(0)
	v_add_f32_e32 v10, v10, v15
	ds_swizzle_b32 v5, v4 offset:swizzle(SWAP,2)
	ds_swizzle_b32 v7, v6 offset:swizzle(SWAP,2)
	ds_swizzle_b32 v9, v8 offset:swizzle(SWAP,2)
	ds_swizzle_b32 v13, v12 offset:swizzle(SWAP,2)
	ds_swizzle_b32 v14, v11 offset:swizzle(SWAP,8)
	ds_swizzle_b32 v15, v10 offset:swizzle(SWAP,2)
	s_waitcnt lgkmcnt(5)
	v_add_f32_e32 v4, v4, v5
	s_waitcnt lgkmcnt(4)
	v_add_f32_e32 v6, v6, v7
	s_waitcnt lgkmcnt(3)
	v_add_f32_e32 v8, v8, v9
	s_waitcnt lgkmcnt(2)
	v_add_f32_e32 v12, v12, v13
	s_waitcnt lgkmcnt(1)
	v_add_f32_e32 v11, v11, v14
	s_waitcnt lgkmcnt(0)
	v_add_f32_e32 v15, v10, v15
	ds_swizzle_b32 v5, v4 offset:swizzle(SWAP,4)
	ds_swizzle_b32 v7, v6 offset:swizzle(SWAP,4)
	ds_swizzle_b32 v9, v8 offset:swizzle(SWAP,4)
	ds_swizzle_b32 v13, v12 offset:swizzle(SWAP,4)
	ds_swizzle_b32 v14, v11 offset:swizzle(SWAP,16)
	ds_swizzle_b32 v16, v15 offset:swizzle(SWAP,4)
	s_waitcnt lgkmcnt(5)
	v_add_f32_e32 v4, v4, v5
	s_waitcnt lgkmcnt(4)
	v_add_f32_e32 v6, v6, v7
	s_waitcnt lgkmcnt(3)
	v_add_f32_e32 v8, v8, v9
	s_waitcnt lgkmcnt(2)
	v_add_f32_e32 v12, v12, v13
	s_waitcnt lgkmcnt(1)
	v_add_f32_e32 v10, v11, v14
	s_waitcnt lgkmcnt(0)
	v_add_f32_e32 v14, v15, v16
	ds_swizzle_b32 v5, v4 offset:swizzle(SWAP,8)
	ds_swizzle_b32 v7, v6 offset:swizzle(SWAP,8)
	ds_swizzle_b32 v9, v8 offset:swizzle(SWAP,8)
	ds_swizzle_b32 v13, v12 offset:swizzle(SWAP,8)
	ds_swizzle_b32 v15, v14 offset:swizzle(SWAP,8)
	s_waitcnt lgkmcnt(4)
	v_add_f32_e32 v4, v4, v5
	s_waitcnt lgkmcnt(3)
	v_add_f32_e32 v6, v6, v7
	s_waitcnt lgkmcnt(2)
	v_add_f32_e32 v8, v8, v9
	s_waitcnt lgkmcnt(1)
	v_add_f32_e32 v12, v12, v13
	s_waitcnt lgkmcnt(0)
	v_add_f32_e32 v14, v14, v15
	ds_swizzle_b32 v3, v2 offset:swizzle(SWAP,16)
	ds_swizzle_b32 v5, v4 offset:swizzle(SWAP,16)
	ds_swizzle_b32 v7, v6 offset:swizzle(SWAP,16)
	ds_swizzle_b32 v9, v8 offset:swizzle(SWAP,16)
	ds_swizzle_b32 v13, v12 offset:swizzle(SWAP,16)
	ds_swizzle_b32 v15, v14 offset:swizzle(SWAP,16)
	s_waitcnt lgkmcnt(5)
	v_add_f32_e32 v2, v2, v3
	s_waitcnt lgkmcnt(4)
	v_add_f32_e32 v4, v4, v5
	s_waitcnt lgkmcnt(3)
	v_add_f32_e32 v6, v6, v7
	s_waitcnt lgkmcnt(2)
	v_add_f32_e32 v8, v8, v9
	s_waitcnt lgkmcnt(1)
	v_add_f32_e32 v12, v12, v13
	s_waitcnt lgkmcnt(0)
	v_add_f32_e32 v14, v14, v15
	v_mov_b32_e32 v1, v0
	v_mov_b32_e32 v3, v2
	v_mov_b32_e32 v5, v4
	v_mov_b32_e32 v7, v6
	v_mov_b32_e32 v9, v8
	v_mov_b32_e32 v11, v10
	v_mov_b32_e32 v13, v12
	v_mov_b32_e32 v15, v14
	v_permlane32_swap_b32_e32 v0, v1
	v_permlane32_swap_b32_e32 v2, v3
	v_permlane32_swap_b32_e32 v4, v5
	v_permlane32_swap_b32_e32 v6, v7
	v_permlane32_swap_b32_e32 v8, v9
	v_permlane32_swap_b32_e32 v10, v11
	v_permlane32_swap_b32_e32 v12, v13
	v_permlane32_swap_b32_e32 v14, v15
	s_and_saveexec_b64 s[4:5], s[6:7]
	s_cbranch_execz .LBB0_527
; __device__ __forceinline__ void norm_phase(ArgP a, LAS unsigned char* lds, int l, bool final_, const int tid, const int bid) {
;     ...
;             float z = fd[0];
; #pragma unroll
;             for (int q = 1; q < 8; ++q) z = (lane == q) ? fd[q] : z;
;             if (lane < 8) { z += a->b_f[l * 8 + lane]; LOGF[(size_t)row * 8 + lane] = fminf(z, 0.f) - log1pf(__expf(-fabsf(z))); }
	v_readlane_b32 s22, v255, 23
	v_readlane_b32 s23, v255, 24
	s_load_dwordx2 s[22:23], s[22:23], 0x30
	v_add_f32_e32 v2, v2, v3
	v_add_f32_e32 v0, v0, v1
	v_add_f32_e32 v4, v4, v5
	v_cndmask_b32_e64 v0, v0, v2, s[20:21]
	s_waitcnt lgkmcnt(0)
	v_lshl_add_u64 v[16:17], v[28:29], 2, s[22:23]
	global_load_dword v16, v[16:17], off
	v_add_f32_e32 v6, v6, v7
	v_cndmask_b32_e64 v0, v0, v4, s[18:19]
	v_add_f32_e32 v8, v8, v9
	v_cndmask_b32_e64 v0, v0, v6, s[16:17]
	v_add_f32_e32 v10, v10, v11
	v_cndmask_b32_e64 v0, v0, v8, s[14:15]
	v_add_f32_e32 v12, v12, v13
	v_cndmask_b32_e64 v0, v0, v10, s[12:13]
	v_add_f32_e32 v14, v14, v15
	v_cndmask_b32_e64 v0, v0, v12, s[10:11]
	v_cndmask_b32_e64 v0, v0, v14, s[8:9]
	s_mov_b32 s22, 0xbfb8aa3b
	s_waitcnt vmcnt(0)
	v_add_f32_e32 v1, v0, v16
	v_mul_f32_e64 v0, |v1|, s22
	v_exp_f32_e32 v0, v0
	s_lshl_b64 s[22:23], s[2:3], 2
	s_mov_b32 s3, 0x3f2aaaab
	v_min_f32_e32 v1, 0, v1
	v_add_f32_e32 v4, 1.0, v0
	v_add_f32_e32 v5, -1.0, v4
	v_frexp_mant_f32_e32 v6, v4
	v_cvt_f64_f32_e32 v[2:3], v4
	v_sub_f32_e32 v7, v5, v4
	v_frexp_exp_i32_f64_e32 v2, v[2:3]
	v_cmp_gt_f32_e32 vcc, s3, v6
	v_sub_f32_e32 v5, v0, v5
	v_add_f32_e32 v3, 1.0, v7
	v_subbrev_co_u32_e32 v2, vcc, 0, v2, vcc
	v_add_f32_e32 v3, v5, v3
	v_sub_u32_e32 v5, 0, v2
	v_ldexp_f32 v4, v4, v5
	v_add_f32_e32 v6, -1.0, v4
	v_add_f32_e32 v7, 1.0, v4
	v_ldexp_f32 v3, v3, v5
	v_add_f32_e32 v5, 1.0, v6
	v_add_f32_e32 v8, -1.0, v7
	v_sub_f32_e32 v5, v4, v5
	v_sub_f32_e32 v4, v4, v8
	v_add_f32_e32 v8, v3, v5
	v_add_f32_e32 v3, v3, v4
	v_add_f32_e32 v10, v7, v3
	v_rcp_f32_e32 v11, v10
	v_add_f32_e32 v5, v6, v8
	v_sub_f32_e32 v6, v5, v6
	v_sub_f32_e32 v4, v10, v7
	v_mul_f32_e32 v13, v5, v11
	v_sub_f32_e32 v12, v8, v6
	v_mul_f32_e32 v6, v10, v13
	v_sub_f32_e32 v3, v3, v4
	v_fma_f32 v8, v13, v10, -v6
	v_fmac_f32_e32 v8, v13, v3
	v_add_f32_e32 v4, v6, v8
	v_sub_f32_e32 v7, v5, v4
	v_mov_b32_e32 v9, v4
	v_pk_add_f32 v[4:5], v[4:5], v[6:7] neg_lo:[0,1] neg_hi:[0,1]
	v_cvt_f32_i32_e32 v2, v2
	v_pk_add_f32 v[4:5], v[4:5], v[8:9] neg_lo:[0,1] neg_hi:[0,1]
	s_mov_b32 s3, 0x3f317218
	v_add_f32_e32 v5, v12, v5
	v_add_f32_e32 v4, v4, v5
	v_add_f32_e32 v5, v7, v4
	v_mul_f32_e32 v9, v11, v5
	v_mul_f32_e32 v6, v10, v9
	v_sub_f32_e32 v7, v7, v5
	v_add_f32_e32 v14, v13, v9
	v_fma_f32 v8, v9, v10, -v6
	v_add_f32_e32 v12, v4, v7
	v_sub_f32_e32 v4, v14, v13
	v_fmac_f32_e32 v8, v9, v3
	v_sub_f32_e32 v3, v9, v4
	v_add_f32_e32 v4, v6, v8
	v_sub_f32_e32 v7, v5, v4
	v_mov_b32_e32 v9, v4
	v_pk_add_f32 v[4:5], v[4:5], v[6:7] neg_lo:[0,1] neg_hi:[0,1]
	s_nop 0
	v_pk_add_f32 v[4:5], v[4:5], v[8:9] neg_lo:[0,1] neg_hi:[0,1]
	v_mov_b32_e32 v8, 0x3ecc95a3
	v_add_f32_e32 v5, v12, v5
	v_add_f32_e32 v4, v4, v5
	v_add_f32_e32 v4, v7, v4
	v_mul_f32_e32 v4, v11, v4
	v_add_f32_e32 v3, v3, v4
	v_add_f32_e32 v4, v14, v3
	v_mul_f32_e32 v6, v4, v4
	v_sub_f32_e32 v7, v4, v14
	v_fmamk_f32 v8, v6, 0x3e9b6dac, v8
	v_sub_f32_e32 v7, v3, v7
	v_mul_f32_e32 v3, v4, v6
	v_fmaak_f32 v183, v6, v8, 0x3f2aaada
	v_ldexp_f32 v9, v7, 1
	v_pk_mul_f32 v[6:7], v[2:3], v[182:183]
	v_ldexp_f32 v5, v4, 1
	v_fma_f32 v4, v2, s3, -v6
	v_fmac_f32_e32 v4, 0xb102e308, v2
	v_pk_add_f32 v[2:3], v[6:7], v[4:5]
	v_mov_b32_e32 v8, v6
	v_sub_f32_e32 v12, v3, v5
	v_pk_add_f32 v[10:11], v[2:3], v[6:7] neg_lo:[0,1] neg_hi:[0,1]
	v_sub_f32_e32 v6, v7, v12
	v_add_f32_e32 v9, v9, v6
	v_pk_add_f32 v[6:7], v[2:3], v[8:9]
	v_mov_b32_e32 v5, v2
	v_mov_b32_e32 v11, v7
	v_pk_add_f32 v[14:15], v[4:5], v[10:11] neg_lo:[0,1] neg_hi:[0,1]
	v_pk_add_f32 v[4:5], v[4:5], v[10:11]
	v_mov_b32_e32 v13, v2
	v_pk_add_f32 v[10:11], v[4:5], v[2:3] op_sel:[1,0] op_sel_hi:[0,1] neg_lo:[0,1] neg_hi:[0,1]
	v_mov_b32_e32 v12, v9
	v_mov_b32_e32 v8, v7
	v_mov_b32_e32 v9, v5
	v_pk_mov_b32 v[2:3], v[2:3], v[10:11] op_sel:[1,0]
	v_pk_add_f32 v[6:7], v[6:7], v[10:11] op_sel_hi:[1,0] neg_lo:[0,1] neg_hi:[0,1]
	v_pk_add_f32 v[2:3], v[8:9], v[2:3] neg_lo:[0,1] neg_hi:[0,1]
	v_mov_b32_e32 v6, v14
	v_pk_add_f32 v[2:3], v[12:13], v[2:3] neg_lo:[0,1] neg_hi:[0,1]
	v_mov_b32_e32 v15, v5
	v_pk_add_f32 v[6:7], v[6:7], v[2:3]
	s_mov_b32 s3, 0x7f800000
	v_pk_add_f32 v[8:9], v[6:7], v[6:7] op_sel:[0,1] op_sel_hi:[1,0]
	v_cmp_neq_f32_e32 vcc, s3, v0
	v_pk_add_f32 v[4:5], v[4:5], v[8:9] op_sel:[1,0] op_sel_hi:[0,1]
	v_mov_b32_e32 v7, v4
	v_mov_b32_e32 v3, v8
	v_pk_add_f32 v[8:9], v[6:7], v[14:15] neg_lo:[0,1] neg_hi:[0,1]
	s_mov_b32 s3, 0x33800000
	v_sub_f32_e32 v5, v6, v8
	v_pk_add_f32 v[2:3], v[2:3], v[8:9] neg_lo:[0,1] neg_hi:[0,1]
	v_sub_f32_e32 v5, v14, v5
	v_add_f32_e32 v2, v2, v5
	v_add_f32_e32 v2, v2, v3
	v_add_f32_e32 v2, v4, v2
	v_cndmask_b32_e32 v2, v201, v2, vcc
	v_cmp_ngt_f32_e32 vcc, -1.0, v0
	s_nop 1
	v_cndmask_b32_e32 v2, v204, v2, vcc
	v_cmp_neq_f32_e32 vcc, -1.0, v0
	s_nop 1
	v_cndmask_b32_e32 v2, v205, v2, vcc
	v_cmp_lt_f32_e64 vcc, |v0|, s3
	s_nop 1
	v_cndmask_b32_e32 v0, v2, v0, vcc
	v_sub_f32_e32 v2, v1, v0
	v_lshl_add_u64 v[0:1], v[30:31], 0, s[22:23]
	global_store_dword v[0:1], v2, off
	s_branch .LBB0_527
